# attention unit copy-out: eight LDS reads issued up front into separate register quads, stores follow with counted lgkmcnt (was read-wait-store serialised through one quad)
# baseline (speedup 1.0000x reference)
.LBB0_249:
	s_andn2_b64 vcc, exec, s[30:31]
	s_waitcnt lgkmcnt(0)
	s_barrier
	s_cbranch_vccnz .LBB0_252
	ds_read2st64_b32 v[66:67], v167 offset1:1
	ds_read2st64_b32 v[68:69], v167 offset0:2 offset1:3
	ds_read2st64_b32 v[70:71], v167 offset0:4 offset1:5
	ds_read2st64_b32 v[72:73], v167 offset0:6 offset1:7
	s_waitcnt lgkmcnt(3)
	v_lshlrev_b32_e32 v74, 16, v66
	v_and_b32_e32 v75, 0xffff0000, v66
	v_lshlrev_b32_e32 v76, 16, v67
	v_and_b32_e32 v77, 0xffff0000, v67
	ds_read2st64_b32 v[66:67], v167 offset0:8 offset1:9
	s_waitcnt lgkmcnt(3)
	v_lshlrev_b32_e32 v78, 16, v68
	v_and_b32_e32 v79, 0xffff0000, v68
	v_lshlrev_b32_e32 v96, 16, v69
	v_and_b32_e32 v97, 0xffff0000, v69
	ds_read2st64_b32 v[68:69], v167 offset0:10 offset1:11
	ds_read2st64_b32 v[102:103], v167 offset0:12 offset1:13
	ds_read2st64_b32 v[104:105], v167 offset0:14 offset1:15
	s_waitcnt lgkmcnt(3)
	v_lshlrev_b32_e32 v106, 16, v66
	v_and_b32_e32 v107, 0xffff0000, v66
	v_lshlrev_b32_e32 v108, 16, v67
	v_and_b32_e32 v109, 0xffff0000, v67
	ds_read2st64_b32 v[66:67], v167 offset0:16 offset1:17
	s_waitcnt lgkmcnt(3)
	v_lshlrev_b32_e32 v110, 16, v68
	v_and_b32_e32 v111, 0xffff0000, v68
	v_lshlrev_b32_e32 v112, 16, v69
	v_and_b32_e32 v113, 0xffff0000, v69
	ds_read2st64_b32 v[68:69], v167 offset0:18 offset1:19
	ds_read2st64_b32 v[118:119], v167 offset0:20 offset1:21
	ds_read2st64_b32 v[120:121], v167 offset0:22 offset1:23
	s_waitcnt lgkmcnt(3)
	v_lshlrev_b32_e32 v122, 16, v66
	v_and_b32_e32 v123, 0xffff0000, v66
	v_lshlrev_b32_e32 v124, 16, v67
	v_and_b32_e32 v125, 0xffff0000, v67
	ds_read2st64_b32 v[66:67], v167 offset0:24 offset1:25
	s_waitcnt lgkmcnt(3)
	v_lshlrev_b32_e32 v126, 16, v68
	v_and_b32_e32 v127, 0xffff0000, v68
	s_waitcnt vmcnt(3)
	v_lshlrev_b32_e32 v128, 16, v69
	v_and_b32_e32 v129, 0xffff0000, v69
	ds_read2st64_b32 v[68:69], v167 offset0:26 offset1:27
	s_waitcnt vmcnt(2)
	ds_read2st64_b32 v[134:135], v167 offset0:28 offset1:29
	s_waitcnt vmcnt(1)
	ds_read2st64_b32 v[136:137], v167 offset0:30 offset1:31
	s_waitcnt lgkmcnt(3)
	v_lshlrev_b32_e32 v138, 16, v66
	v_and_b32_e32 v139, 0xffff0000, v66
	s_waitcnt vmcnt(0)
	v_lshlrev_b32_e32 v140, 16, v67
	v_and_b32_e32 v141, 0xffff0000, v67
	v_mov_b32_e32 v66, v52
	v_mov_b32_e32 v67, v54
	v_mov_b32_e32 v54, v53
	s_waitcnt lgkmcnt(2)
	v_and_b32_e32 v53, 0xffff0000, v69
	v_and_b32_e32 v52, 0xffff0000, v68
	v_lshlrev_b32_e32 v143, 16, v69
	v_lshlrev_b32_e32 v142, 16, v68
	v_pk_fma_f32 v[68:69], v[54:55], v[64:65], v[52:53] op_sel_hi:[1,0,1]
	v_pk_fma_f32 v[66:67], v[66:67], v[64:65], v[142:143] op_sel_hi:[1,0,1]
	v_pk_mul_f32 v[52:53], v[68:69], v[68:69]
	s_waitcnt lgkmcnt(1)
	v_lshlrev_b32_e32 v55, 16, v135
	v_pk_fma_f32 v[142:143], v[66:67], v[66:67], v[52:53]
	v_mov_b32_e32 v52, v56
	v_mov_b32_e32 v53, v58
	v_lshlrev_b32_e32 v54, 16, v134
	v_pk_fma_f32 v[52:53], v[52:53], v[64:65], v[54:55] op_sel_hi:[1,0,1]
	v_mov_b32_e32 v58, v57
	v_and_b32_e32 v55, 0xffff0000, v135
	v_and_b32_e32 v54, 0xffff0000, v134
	v_pk_fma_f32 v[56:57], v[58:59], v[64:65], v[54:55] op_sel_hi:[1,0,1]
	s_waitcnt lgkmcnt(0)
	v_lshlrev_b32_e32 v59, 16, v137
	v_pk_mul_f32 v[54:55], v[56:57], v[56:57]
	v_lshlrev_b32_e32 v58, 16, v136
	v_pk_fma_f32 v[134:135], v[52:53], v[52:53], v[54:55]
	v_mov_b32_e32 v54, v60
	v_mov_b32_e32 v55, v62
	v_pk_fma_f32 v[54:55], v[54:55], v[64:65], v[58:59] op_sel_hi:[1,0,1]
	v_mov_b32_e32 v62, v61
	v_and_b32_e32 v59, 0xffff0000, v137
	v_and_b32_e32 v58, 0xffff0000, v136
	v_pk_fma_f32 v[34:35], v[34:35], v[64:65], v[76:77] op_sel_hi:[1,0,1]
	v_pk_fma_f32 v[32:33], v[32:33], v[64:65], v[74:75] op_sel_hi:[1,0,1]
	v_pk_fma_f32 v[58:59], v[62:63], v[64:65], v[58:59] op_sel_hi:[1,0,1]
	v_pk_mul_f32 v[62:63], v[34:35], v[34:35]
	v_pk_mul_f32 v[74:75], v[32:33], v[32:33]
	v_pk_fma_f32 v[36:37], v[36:37], v[64:65], v[78:79] op_sel_hi:[1,0,1]
	v_lshlrev_b32_e32 v98, 16, v70
	v_and_b32_e32 v99, 0xffff0000, v70
	v_pk_fma_f32 v[38:39], v[38:39], v[64:65], v[96:97] op_sel_hi:[1,0,1]
	v_pk_mul_f32 v[78:79], v[36:37], v[36:37]
	v_add_f32_e32 v62, v62, v63
	v_add_f32_e32 v63, v74, v75
	v_lshlrev_b32_e32 v70, 16, v71
	v_and_b32_e32 v71, 0xffff0000, v71
	v_pk_mul_f32 v[76:77], v[38:39], v[38:39]
	v_pk_fma_f32 v[40:41], v[40:41], v[64:65], v[98:99] op_sel_hi:[1,0,1]
	v_add_f32_e32 v62, v63, v62
	v_add_f32_e32 v63, v78, v79
	v_lshlrev_b32_e32 v100, 16, v72
	v_and_b32_e32 v101, 0xffff0000, v72
	v_pk_fma_f32 v[42:43], v[42:43], v[64:65], v[70:71] op_sel_hi:[1,0,1]
	v_pk_mul_f32 v[96:97], v[40:41], v[40:41]
	v_add_f32_e32 v62, v62, v63
	v_add_f32_e32 v63, v76, v77
	v_lshlrev_b32_e32 v72, 16, v73
	v_and_b32_e32 v73, 0xffff0000, v73
	v_pk_mul_f32 v[70:71], v[42:43], v[42:43]
	v_pk_fma_f32 v[44:45], v[44:45], v[64:65], v[100:101] op_sel_hi:[1,0,1]
	v_add_f32_e32 v62, v62, v63
	v_add_f32_e32 v63, v96, v97
	v_pk_fma_f32 v[46:47], v[46:47], v[64:65], v[72:73] op_sel_hi:[1,0,1]
	v_pk_mul_f32 v[98:99], v[44:45], v[44:45]
	v_add_f32_e32 v62, v62, v63
	v_add_f32_e32 v63, v70, v71
	v_pk_mul_f32 v[72:73], v[46:47], v[46:47]
	v_pk_fma_f32 v[16:17], v[16:17], v[64:65], v[106:107] op_sel_hi:[1,0,1]
	v_add_f32_e32 v62, v62, v63
	v_add_f32_e32 v63, v98, v99
	v_pk_fma_f32 v[18:19], v[18:19], v[64:65], v[108:109] op_sel_hi:[1,0,1]
	v_pk_mul_f32 v[106:107], v[16:17], v[16:17]
	v_add_f32_e32 v62, v62, v63
	v_add_f32_e32 v63, v72, v73
	v_pk_mul_f32 v[100:101], v[18:19], v[18:19]
	v_pk_fma_f32 v[20:21], v[20:21], v[64:65], v[110:111] op_sel_hi:[1,0,1]
	v_add_f32_e32 v62, v62, v63
	v_add_f32_e32 v63, v106, v107
	v_lshlrev_b32_e32 v114, 16, v102
	v_and_b32_e32 v115, 0xffff0000, v102
	v_pk_fma_f32 v[22:23], v[22:23], v[64:65], v[112:113] op_sel_hi:[1,0,1]
	v_pk_mul_f32 v[110:111], v[20:21], v[20:21]
	v_add_f32_e32 v62, v62, v63
	v_add_f32_e32 v63, v100, v101
	v_lshlrev_b32_e32 v102, 16, v103
	v_and_b32_e32 v103, 0xffff0000, v103
	v_pk_mul_f32 v[108:109], v[22:23], v[22:23]
	v_pk_fma_f32 v[24:25], v[24:25], v[64:65], v[114:115] op_sel_hi:[1,0,1]
	v_add_f32_e32 v62, v62, v63
	v_add_f32_e32 v63, v110, v111
	v_lshlrev_b32_e32 v116, 16, v104
	v_and_b32_e32 v117, 0xffff0000, v104
	v_pk_fma_f32 v[26:27], v[26:27], v[64:65], v[102:103] op_sel_hi:[1,0,1]
	v_pk_mul_f32 v[112:113], v[24:25], v[24:25]
	v_add_f32_e32 v62, v62, v63
	v_add_f32_e32 v63, v108, v109
	v_lshlrev_b32_e32 v104, 16, v105
	v_and_b32_e32 v105, 0xffff0000, v105
	v_pk_mul_f32 v[102:103], v[26:27], v[26:27]
	v_pk_fma_f32 v[28:29], v[28:29], v[64:65], v[116:117] op_sel_hi:[1,0,1]
	v_add_f32_e32 v62, v62, v63
	v_add_f32_e32 v63, v112, v113
	v_pk_fma_f32 v[30:31], v[30:31], v[64:65], v[104:105] op_sel_hi:[1,0,1]
	v_pk_mul_f32 v[114:115], v[28:29], v[28:29]
	v_add_f32_e32 v62, v62, v63
	v_add_f32_e32 v63, v102, v103
	v_pk_mul_f32 v[104:105], v[30:31], v[30:31]
	v_pk_fma_f32 v[0:1], v[0:1], v[64:65], v[122:123] op_sel_hi:[1,0,1]
	v_add_f32_e32 v62, v62, v63
	v_add_f32_e32 v63, v114, v115
	v_pk_fma_f32 v[2:3], v[2:3], v[64:65], v[124:125] op_sel_hi:[1,0,1]
	v_pk_mul_f32 v[122:123], v[0:1], v[0:1]
	v_add_f32_e32 v62, v62, v63
	v_add_f32_e32 v63, v104, v105
	v_pk_mul_f32 v[116:117], v[2:3], v[2:3]
	v_pk_fma_f32 v[4:5], v[4:5], v[64:65], v[126:127] op_sel_hi:[1,0,1]
	v_add_f32_e32 v62, v62, v63
	v_add_f32_e32 v63, v122, v123
	v_lshlrev_b32_e32 v130, 16, v118
	v_and_b32_e32 v131, 0xffff0000, v118
	v_pk_fma_f32 v[6:7], v[6:7], v[64:65], v[128:129] op_sel_hi:[1,0,1]
	v_pk_mul_f32 v[126:127], v[4:5], v[4:5]
	v_add_f32_e32 v62, v62, v63
	v_add_f32_e32 v63, v116, v117
	v_lshlrev_b32_e32 v118, 16, v119
	v_and_b32_e32 v119, 0xffff0000, v119
	v_lshlrev_b32_e32 v132, 16, v120
	v_and_b32_e32 v133, 0xffff0000, v120
	v_lshlrev_b32_e32 v120, 16, v121
	v_and_b32_e32 v121, 0xffff0000, v121
	v_pk_mul_f32 v[124:125], v[6:7], v[6:7]
	v_pk_fma_f32 v[8:9], v[8:9], v[64:65], v[130:131] op_sel_hi:[1,0,1]
	v_add_f32_e32 v62, v62, v63
	v_add_f32_e32 v63, v126, v127
	v_pk_fma_f32 v[10:11], v[10:11], v[64:65], v[118:119] op_sel_hi:[1,0,1]
	v_pk_mul_f32 v[128:129], v[8:9], v[8:9]
	v_pk_fma_f32 v[14:15], v[14:15], v[64:65], v[120:121] op_sel_hi:[1,0,1]
	v_pk_fma_f32 v[12:13], v[12:13], v[64:65], v[132:133] op_sel_hi:[1,0,1]
	v_add_f32_e32 v62, v62, v63
	v_add_f32_e32 v63, v124, v125
	v_pk_mul_f32 v[118:119], v[10:11], v[10:11]
	v_mov_b32_e32 v130, v13
	v_mov_b32_e32 v131, v15
	v_add_f32_e32 v62, v62, v63
	v_add_f32_e32 v63, v128, v129
	v_mov_b32_e32 v120, v12
	v_mov_b32_e32 v121, v14
	v_pk_mul_f32 v[130:131], v[130:131], v[130:131]
	v_pk_fma_f32 v[50:51], v[50:51], v[64:65], v[140:141] op_sel_hi:[1,0,1]
	v_pk_fma_f32 v[48:49], v[48:49], v[64:65], v[138:139] op_sel_hi:[1,0,1]
	v_add_f32_e32 v62, v62, v63
	v_add_f32_e32 v63, v118, v119
	v_pk_fma_f32 v[120:121], v[120:121], v[120:121], v[130:131]
	v_mov_b32_e32 v130, v49
	v_mov_b32_e32 v131, v51
	v_add_f32_e32 v62, v62, v63
	v_mov_b32_e32 v64, v48
	v_mov_b32_e32 v65, v50
	v_pk_mul_f32 v[130:131], v[130:131], v[130:131]
	v_add_f32_e32 v62, v62, v120
	v_pk_fma_f32 v[64:65], v[64:65], v[64:65], v[130:131]
	v_add_f32_e32 v62, v62, v121
	v_add_f32_e32 v62, v62, v64
	v_add_f32_e32 v62, v62, v65
	v_add_f32_e32 v62, v62, v142
	v_add_f32_e32 v62, v62, v143
	v_pk_mul_f32 v[60:61], v[58:59], v[58:59]
	v_add_f32_e32 v62, v62, v134
	v_pk_fma_f32 v[60:61], v[54:55], v[54:55], v[60:61]
	v_add_f32_e32 v62, v62, v135
	v_add_f32_e32 v60, v62, v60
	v_add_f32_e32 v60, v60, v61
	ds_bpermute_b32 v61, v155, v60
	s_waitcnt lgkmcnt(0)
	v_add_f32_e32 v60, v60, v61
	v_fmamk_f32 v60, v60, 0x3c000000, v236
	v_mul_f32_e32 v61, 0x4b800000, v60
	v_cmp_gt_f32_e32 vcc, s3, v60
	s_nop 1
	v_cndmask_b32_e32 v60, v60, v61, vcc
	v_rsq_f32_e32 v60, v60
	s_nop 0
	v_mul_f32_e32 v61, 0x45800000, v60
	v_cndmask_b32_e32 v60, v60, v61, vcc
	v_pk_mul_f32 v[0:1], v[0:1], v[60:61] op_sel_hi:[1,0]
	v_pk_mul_f32 v[2:3], v[2:3], v[60:61] op_sel_hi:[1,0]
	v_cvt_pk_bf16_f32 v0, v0, v1
	v_cvt_pk_bf16_f32 v1, v2, v3
	v_pk_mul_f32 v[2:3], v[4:5], v[60:61] op_sel_hi:[1,0]
	v_pk_mul_f32 v[4:5], v[6:7], v[60:61] op_sel_hi:[1,0]
	v_cvt_pk_bf16_f32 v2, v2, v3
	v_cvt_pk_bf16_f32 v3, v4, v5
	ds_write2_b64 v169, v[0:1], v[2:3] offset0:16 offset1:18
	v_pk_mul_f32 v[0:1], v[8:9], v[60:61] op_sel_hi:[1,0]
	v_pk_mul_f32 v[2:3], v[10:11], v[60:61] op_sel_hi:[1,0]
	v_cvt_pk_bf16_f32 v0, v0, v1
	v_cvt_pk_bf16_f32 v1, v2, v3
	v_pk_mul_f32 v[2:3], v[12:13], v[60:61] op_sel_hi:[1,0]
	v_pk_mul_f32 v[4:5], v[14:15], v[60:61] op_sel_hi:[1,0]
	v_cvt_pk_bf16_f32 v2, v2, v3
	v_cvt_pk_bf16_f32 v3, v4, v5
	ds_write2_b64 v169, v[0:1], v[2:3] offset0:20 offset1:22
	v_pk_mul_f32 v[0:1], v[48:49], v[60:61] op_sel_hi:[1,0]
	v_pk_mul_f32 v[2:3], v[50:51], v[60:61] op_sel_hi:[1,0]
	v_cvt_pk_bf16_f32 v0, v0, v1
	v_cvt_pk_bf16_f32 v1, v2, v3
	v_mov_b32_e32 v2, v66
	v_mov_b32_e32 v3, v68
	v_mov_b32_e32 v68, v67
	v_pk_mul_f32 v[2:3], v[2:3], v[60:61] op_sel_hi:[1,0]
	v_pk_mul_f32 v[4:5], v[68:69], v[60:61] op_sel_hi:[1,0]
	v_pk_mul_f32 v[32:33], v[32:33], v[60:61] op_sel_hi:[1,0]
	v_pk_mul_f32 v[34:35], v[34:35], v[60:61] op_sel_hi:[1,0]
	v_pk_mul_f32 v[16:17], v[16:17], v[60:61] op_sel_hi:[1,0]
	v_pk_mul_f32 v[18:19], v[18:19], v[60:61] op_sel_hi:[1,0]
	v_cvt_pk_bf16_f32 v2, v2, v3
	v_cvt_pk_bf16_f32 v3, v4, v5
	v_cvt_pk_bf16_f32 v32, v32, v33
	v_cvt_pk_bf16_f32 v33, v34, v35
	v_pk_mul_f32 v[34:35], v[36:37], v[60:61] op_sel_hi:[1,0]
	v_pk_mul_f32 v[36:37], v[38:39], v[60:61] op_sel_hi:[1,0]
	v_cvt_pk_bf16_f32 v16, v16, v17
	v_cvt_pk_bf16_f32 v17, v18, v19
	v_pk_mul_f32 v[18:19], v[20:21], v[60:61] op_sel_hi:[1,0]
	v_pk_mul_f32 v[20:21], v[22:23], v[60:61] op_sel_hi:[1,0]
	ds_write2_b64 v169, v[0:1], v[2:3] offset0:24 offset1:26
	v_mov_b32_e32 v0, v52
	v_mov_b32_e32 v1, v56
	v_mov_b32_e32 v56, v53
	v_cvt_pk_bf16_f32 v34, v34, v35
	v_cvt_pk_bf16_f32 v35, v36, v37
	v_cvt_pk_bf16_f32 v18, v18, v19
	v_cvt_pk_bf16_f32 v19, v20, v21
	v_pk_mul_f32 v[0:1], v[0:1], v[60:61] op_sel_hi:[1,0]
	v_pk_mul_f32 v[2:3], v[56:57], v[60:61] op_sel_hi:[1,0]
	ds_write2_b64 v169, v[32:33], v[34:35] offset1:2
	v_pk_mul_f32 v[32:33], v[40:41], v[60:61] op_sel_hi:[1,0]
	v_pk_mul_f32 v[34:35], v[42:43], v[60:61] op_sel_hi:[1,0]
	ds_write2_b64 v169, v[16:17], v[18:19] offset0:8 offset1:10
	v_pk_mul_f32 v[16:17], v[24:25], v[60:61] op_sel_hi:[1,0]
	v_pk_mul_f32 v[18:19], v[26:27], v[60:61] op_sel_hi:[1,0]
	v_cvt_pk_bf16_f32 v0, v0, v1
	v_cvt_pk_bf16_f32 v1, v2, v3
	v_mov_b32_e32 v2, v54
	v_mov_b32_e32 v3, v58
	v_mov_b32_e32 v58, v55
	v_cvt_pk_bf16_f32 v32, v32, v33
	v_cvt_pk_bf16_f32 v33, v34, v35
	v_pk_mul_f32 v[34:35], v[44:45], v[60:61] op_sel_hi:[1,0]
	v_pk_mul_f32 v[36:37], v[46:47], v[60:61] op_sel_hi:[1,0]
	v_cvt_pk_bf16_f32 v16, v16, v17
	v_cvt_pk_bf16_f32 v17, v18, v19
	v_pk_mul_f32 v[18:19], v[28:29], v[60:61] op_sel_hi:[1,0]
	v_pk_mul_f32 v[20:21], v[30:31], v[60:61] op_sel_hi:[1,0]
	v_pk_mul_f32 v[2:3], v[2:3], v[60:61] op_sel_hi:[1,0]
	v_pk_mul_f32 v[4:5], v[58:59], v[60:61] op_sel_hi:[1,0]
	v_cvt_pk_bf16_f32 v34, v34, v35
	v_cvt_pk_bf16_f32 v35, v36, v37
	v_cvt_pk_bf16_f32 v18, v18, v19
	v_cvt_pk_bf16_f32 v19, v20, v21
	v_cvt_pk_bf16_f32 v2, v2, v3
	v_cvt_pk_bf16_f32 v3, v4, v5
	ds_write2_b64 v169, v[32:33], v[34:35] offset0:4 offset1:6
	ds_write2_b64 v169, v[16:17], v[18:19] offset0:12 offset1:14
	ds_write2_b64 v169, v[0:1], v[2:3] offset0:28 offset1:30
	s_waitcnt lgkmcnt(0)
	s_andn2_b64 vcc, exec, s[40:41]
	s_cbranch_vccnz .LBB0_252
	ds_read_b128 v[0:3], v196
	ds_read_b128 v[8:11], v197
	ds_read_b128 v[12:15], v198
	ds_read_b128 v[16:19], v199
	ds_read_b128 v[20:23], v200
	ds_read_b128 v[24:27], v201
	ds_read_b128 v[28:31], v202
	ds_read_b128 v[32:35], v203
	s_lshl_b32 s66, s89, 1
	v_lshl_add_u64 v[4:5], v[152:153], 0, s[66:67]
	v_mov_b32_e32 v7, s63
	v_or_b32_e32 v6, s62, v154
	v_lshlrev_b64 v[6:7], 11, v[6:7]
	v_lshl_add_u64 v[6:7], v[4:5], 0, v[6:7]
	s_waitcnt lgkmcnt(7)
	global_store_dwordx4 v[6:7], v[0:3], off
	s_nop 0
	v_mov_b32_e32 v7, s63
	v_or_b32_e32 v6, s62, v156
	v_lshlrev_b64 v[6:7], 11, v[6:7]
	v_lshl_add_u64 v[6:7], v[4:5], 0, v[6:7]
	s_waitcnt lgkmcnt(6)
	global_store_dwordx4 v[6:7], v[8:11], off
	s_nop 0
	v_mov_b32_e32 v7, s63
	v_or_b32_e32 v6, s62, v158
	v_lshlrev_b64 v[6:7], 11, v[6:7]
	v_lshl_add_u64 v[6:7], v[4:5], 0, v[6:7]
	s_waitcnt lgkmcnt(5)
	global_store_dwordx4 v[6:7], v[12:15], off
	s_nop 0
	v_mov_b32_e32 v7, s63
	v_or_b32_e32 v6, s62, v160
	v_lshlrev_b64 v[6:7], 11, v[6:7]
	v_lshl_add_u64 v[6:7], v[4:5], 0, v[6:7]
	s_waitcnt lgkmcnt(4)
	global_store_dwordx4 v[6:7], v[16:19], off
	s_nop 0
	v_mov_b32_e32 v7, s63
	v_or_b32_e32 v6, s62, v162
	v_lshlrev_b64 v[6:7], 11, v[6:7]
	v_lshl_add_u64 v[6:7], v[4:5], 0, v[6:7]
	s_waitcnt lgkmcnt(3)
	global_store_dwordx4 v[6:7], v[20:23], off
	s_nop 0
	v_mov_b32_e32 v7, s63
	v_or_b32_e32 v6, s62, v164
	v_lshlrev_b64 v[6:7], 11, v[6:7]
	v_lshl_add_u64 v[6:7], v[4:5], 0, v[6:7]
	s_waitcnt lgkmcnt(2)
	global_store_dwordx4 v[6:7], v[24:27], off
	s_nop 0
	v_mov_b32_e32 v7, s63
	v_or_b32_e32 v6, s62, v166
	v_lshlrev_b64 v[6:7], 11, v[6:7]
	v_lshl_add_u64 v[6:7], v[4:5], 0, v[6:7]
	s_waitcnt lgkmcnt(1)
	global_store_dwordx4 v[6:7], v[28:31], off
	s_nop 0
	v_mov_b32_e32 v7, s63
	v_or_b32_e32 v6, s62, v168
	v_lshlrev_b64 v[6:7], 11, v[6:7]
	v_lshl_add_u64 v[4:5], v[4:5], 0, v[6:7]
	s_waitcnt lgkmcnt(0)
	global_store_dwordx4 v[4:5], v[32:35], off
